# row passes: residual-stream X stores also non-temporal
# speedup vs baseline: 1.0214x; 1.0011x over previous
.Lrp10_go0:
	v_lshlrev_b32_e32 v100, 16, v204
	v_and_b32_e32 v101, 0xffff0000, v204
	v_lshlrev_b32_e32 v102, 16, v205
	v_and_b32_e32 v103, 0xffff0000, v205
	v_lshlrev_b32_e32 v104, 16, v206
	v_and_b32_e32 v105, 0xffff0000, v206
	v_lshlrev_b32_e32 v106, 16, v207
	v_and_b32_e32 v107, 0xffff0000, v207
	v_lshlrev_b32_e32 v108, 16, v208
	v_and_b32_e32 v109, 0xffff0000, v208
	v_lshlrev_b32_e32 v110, 16, v209
	v_and_b32_e32 v111, 0xffff0000, v209
	v_lshlrev_b32_e32 v112, 16, v210
	v_and_b32_e32 v113, 0xffff0000, v210
	v_lshlrev_b32_e32 v114, 16, v211
	v_and_b32_e32 v115, 0xffff0000, v211
	v_mul_f32_e32 v132, v100, v100
	v_mul_f32_e32 v133, v101, v101
	v_fmac_f32_e32 v132, v102, v102
	v_fmac_f32_e32 v133, v103, v103
	v_fmac_f32_e32 v132, v104, v104
	v_fmac_f32_e32 v133, v105, v105
	v_fmac_f32_e32 v132, v106, v106
	v_fmac_f32_e32 v133, v107, v107
	v_fmac_f32_e32 v132, v108, v108
	v_fmac_f32_e32 v133, v109, v109
	v_fmac_f32_e32 v132, v110, v110
	v_fmac_f32_e32 v133, v111, v111
	v_fmac_f32_e32 v132, v112, v112
	v_fmac_f32_e32 v133, v113, v113
	v_fmac_f32_e32 v132, v114, v114
	v_fmac_f32_e32 v133, v115, v115
	v_add_f32_e32 v132, v132, v133
	s_nop 1
	v_add_f32_dpp v132, v132, v132 quad_perm:[1,0,3,2] row_mask:0xf bank_mask:0xf bound_ctrl:1
	s_nop 1
	v_add_f32_dpp v132, v132, v132 quad_perm:[2,3,0,1] row_mask:0xf bank_mask:0xf bound_ctrl:1
	s_nop 1
	v_add_f32_dpp v132, v132, v132 row_ror:4 row_mask:0xf bank_mask:0xf bound_ctrl:1
	s_nop 1
	v_add_f32_dpp v132, v132, v132 row_ror:8 row_mask:0xf bank_mask:0xf bound_ctrl:1
	s_nop 1
	v_readlane_b32 s9, v132, 0
	v_readlane_b32 s38, v132, 16
	v_readlane_b32 s39, v132, 32
	v_readlane_b32 s40, v132, 48
	s_nop 2
	v_mov_b32_e32 v132, s9
	v_add_f32_e32 v132, s38, v132
	v_mov_b32_e32 v135, s39
	v_add_f32_e32 v135, s40, v135
	v_add_f32_e32 v132, v132, v135
	v_fmamk_f32 v132, v132, 0x3a800000, v238
	v_rsq_f32_e32 v132, v132
	s_nop 0
	v_mul_f32_e32 v100, v100, v132
	v_mul_f32_e32 v101, v101, v132
	v_mul_f32_e32 v102, v102, v132
	v_mul_f32_e32 v103, v103, v132
	v_mul_f32_e32 v104, v104, v132
	v_mul_f32_e32 v105, v105, v132
	v_mul_f32_e32 v106, v106, v132
	v_mul_f32_e32 v107, v107, v132
	v_mul_f32_e32 v108, v108, v132
	v_mul_f32_e32 v109, v109, v132
	v_mul_f32_e32 v110, v110, v132
	v_mul_f32_e32 v111, v111, v132
	v_mul_f32_e32 v112, v112, v132
	v_mul_f32_e32 v113, v113, v132
	v_mul_f32_e32 v114, v114, v132
	v_mul_f32_e32 v115, v115, v132
	v_fmac_f32_e32 v188, v140, v100
	v_fmac_f32_e32 v189, v141, v101
	v_fmac_f32_e32 v190, v142, v102
	v_fmac_f32_e32 v191, v143, v103
	v_fmac_f32_e32 v192, v144, v104
	v_fmac_f32_e32 v193, v145, v105
	v_fmac_f32_e32 v194, v146, v106
	v_fmac_f32_e32 v195, v147, v107
	v_fmac_f32_e32 v196, v148, v108
	v_fmac_f32_e32 v197, v149, v109
	v_fmac_f32_e32 v198, v150, v110
	v_fmac_f32_e32 v199, v151, v111
	v_fmac_f32_e32 v200, v152, v112
	v_fmac_f32_e32 v201, v153, v113
	v_fmac_f32_e32 v202, v154, v114
	v_fmac_f32_e32 v203, v155, v115
	global_store_dwordx4 v236, v[188:191], s[32:33] offset:0 nt
	global_store_dwordx4 v236, v[192:195], s[32:33] offset:1024 nt
	global_store_dwordx4 v236, v[196:199], s[32:33] offset:2048 nt
	global_store_dwordx4 v236, v[200:203], s[32:33] offset:3072 nt
	v_mul_f32_e32 v132, v188, v188
	v_mul_f32_e32 v133, v189, v189
	v_fmac_f32_e32 v132, v190, v190
	v_fmac_f32_e32 v133, v191, v191
	v_fmac_f32_e32 v132, v192, v192
	v_fmac_f32_e32 v133, v193, v193
	v_fmac_f32_e32 v132, v194, v194
	v_fmac_f32_e32 v133, v195, v195
	v_fmac_f32_e32 v132, v196, v196
	v_fmac_f32_e32 v133, v197, v197
	v_fmac_f32_e32 v132, v198, v198
	v_fmac_f32_e32 v133, v199, v199
	v_fmac_f32_e32 v132, v200, v200
	v_fmac_f32_e32 v133, v201, v201
	v_fmac_f32_e32 v132, v202, v202
	v_fmac_f32_e32 v133, v203, v203
	v_add_f32_e32 v132, v132, v133
	s_nop 1
	v_add_f32_dpp v132, v132, v132 quad_perm:[1,0,3,2] row_mask:0xf bank_mask:0xf bound_ctrl:1
	s_nop 1
	v_add_f32_dpp v132, v132, v132 quad_perm:[2,3,0,1] row_mask:0xf bank_mask:0xf bound_ctrl:1
	s_nop 1
	v_add_f32_dpp v132, v132, v132 row_ror:4 row_mask:0xf bank_mask:0xf bound_ctrl:1
	s_nop 1
	v_add_f32_dpp v132, v132, v132 row_ror:8 row_mask:0xf bank_mask:0xf bound_ctrl:1
	s_nop 1
	v_readlane_b32 s9, v132, 0
	v_readlane_b32 s38, v132, 16
	v_readlane_b32 s39, v132, 32
	v_readlane_b32 s40, v132, 48
	s_nop 2
	v_mov_b32_e32 v132, s9
	v_add_f32_e32 v132, s38, v132
	v_mov_b32_e32 v135, s39
	v_add_f32_e32 v135, s40, v135
	v_add_f32_e32 v132, v132, v135
	v_fmamk_f32 v132, v132, 0x3a800000, v238
	v_rsq_f32_e32 v132, v132
	s_nop 0
	v_mul_f32_e32 v116, v188, v132
	v_mul_f32_e32 v117, v189, v132
	v_mul_f32_e32 v118, v190, v132
	v_mul_f32_e32 v119, v191, v132
	v_mul_f32_e32 v120, v192, v132
	v_mul_f32_e32 v121, v193, v132
	v_mul_f32_e32 v122, v194, v132
	v_mul_f32_e32 v123, v195, v132
	v_mul_f32_e32 v124, v196, v132
	v_mul_f32_e32 v125, v197, v132
	v_mul_f32_e32 v126, v198, v132
	v_mul_f32_e32 v127, v199, v132
	v_mul_f32_e32 v128, v200, v132
	v_mul_f32_e32 v129, v201, v132
	v_mul_f32_e32 v130, v202, v132
	v_mul_f32_e32 v131, v203, v132
	v_fma_f32 v116, v116, v156, v172
	v_fma_f32 v117, v117, v157, v173
	v_fma_f32 v118, v118, v158, v174
	v_fma_f32 v119, v119, v159, v175
	v_fma_f32 v120, v120, v160, v176
	v_fma_f32 v121, v121, v161, v177
	v_fma_f32 v122, v122, v162, v178
	v_fma_f32 v123, v123, v163, v179
	v_fma_f32 v124, v124, v164, v180
	v_fma_f32 v125, v125, v165, v181
	v_fma_f32 v126, v126, v166, v182
	v_fma_f32 v127, v127, v167, v183
	v_fma_f32 v128, v128, v168, v184
	v_fma_f32 v129, v129, v169, v185
	v_fma_f32 v130, v130, v170, v186
	v_fma_f32 v131, v131, v171, v187
	v_cvt_pk_bf16_f32 v116, v116, v117
	v_cvt_pk_bf16_f32 v117, v118, v119
	v_cvt_pk_bf16_f32 v118, v120, v121
	v_cvt_pk_bf16_f32 v119, v122, v123
	v_cvt_pk_bf16_f32 v120, v124, v125
	v_cvt_pk_bf16_f32 v121, v126, v127
	v_cvt_pk_bf16_f32 v122, v128, v129
	v_cvt_pk_bf16_f32 v123, v130, v131
	global_store_dwordx2 v237, v[116:117], s[34:35] offset:0
	global_store_dwordx2 v237, v[118:119], s[34:35] offset:512
	global_store_dwordx2 v237, v[120:121], s[34:35] offset:1024
	global_store_dwordx2 v237, v[122:123], s[34:35] offset:1536
	s_cmp_lt_u32 s6, s7
	s_cbranch_scc0 .Lrp10_done
	s_sub_u32 s9, s6, 0x2000
	s_ashr_i32 s9, s9, 10
	s_add_i32 s9, s9, 1
	s_max_i32 s9, s9, 0
	s_cmp_eq_u32 s9, s8
	s_cbranch_scc1 .Lrp10_same1
	s_mov_b32 s8, s9
	s_add_i32 s9, s8, 0
	s_mul_i32 s9, s9, 0x6000
	s_add_u32 s36, s22, s9
	s_addc_u32 s37, s23, 0
	s_add_u32 s38, s36, 0x2000
	s_addc_u32 s39, s37, 0
	global_load_dwordx4 v[32:35], v236, s[38:39] offset:0
	global_load_dwordx4 v[36:39], v236, s[38:39] offset:1024
	global_load_dwordx4 v[40:43], v236, s[38:39] offset:2048
	global_load_dwordx4 v[44:47], v236, s[38:39] offset:3072
	global_load_dwordx4 v[48:51], v236, s[10:11] offset:0
	global_load_dwordx4 v[52:55], v236, s[10:11] offset:1024
	global_load_dwordx4 v[56:59], v236, s[10:11] offset:2048
	global_load_dwordx4 v[64:67], v236, s[10:11] offset:3072
	global_load_dwordx4 v[68:71], v236, s[12:13] offset:0
	global_load_dwordx4 v[72:75], v236, s[12:13] offset:1024
	global_load_dwordx4 v[76:79], v236, s[12:13] offset:2048
	global_load_dwordx4 v[100:103], v236, s[12:13] offset:3072
	s_add_u32 s38, s36, 0x4000
	s_addc_u32 s39, s37, 0
	global_load_dwordx4 v[104:107], v236, s[38:39] offset:0
	global_load_dwordx4 v[108:111], v236, s[38:39] offset:1024
	global_load_dwordx4 v[112:115], v236, s[38:39] offset:2048
	global_load_dwordx4 v[116:119], v236, s[38:39] offset:3072
	s_add_u32 s38, s36, 0x3000
	s_addc_u32 s39, s37, 0
	global_load_dwordx4 v[172:175], v236, s[38:39] offset:0
	global_load_dwordx4 v[176:179], v236, s[38:39] offset:1024
	global_load_dwordx4 v[180:183], v236, s[38:39] offset:2048
	global_load_dwordx4 v[184:187], v236, s[38:39] offset:3072
	s_waitcnt vmcnt(0)
	v_mul_f32_e32 v140, v32, v48
	v_mul_f32_e32 v141, v33, v49
	v_mul_f32_e32 v142, v34, v50
	v_mul_f32_e32 v143, v35, v51
	v_mul_f32_e32 v144, v36, v52
	v_mul_f32_e32 v145, v37, v53
	v_mul_f32_e32 v146, v38, v54
	v_mul_f32_e32 v147, v39, v55
	v_mul_f32_e32 v148, v40, v56
	v_mul_f32_e32 v149, v41, v57
	v_mul_f32_e32 v150, v42, v58
	v_mul_f32_e32 v151, v43, v59
	v_mul_f32_e32 v152, v44, v64
	v_mul_f32_e32 v153, v45, v65
	v_mul_f32_e32 v154, v46, v66
	v_mul_f32_e32 v155, v47, v67
	v_add_f32_e32 v104, 1.0, v104
	v_add_f32_e32 v105, 1.0, v105
	v_add_f32_e32 v106, 1.0, v106
	v_add_f32_e32 v107, 1.0, v107
	v_add_f32_e32 v108, 1.0, v108
	v_add_f32_e32 v109, 1.0, v109
	v_add_f32_e32 v110, 1.0, v110
	v_add_f32_e32 v111, 1.0, v111
	v_add_f32_e32 v112, 1.0, v112
	v_add_f32_e32 v113, 1.0, v113
	v_add_f32_e32 v114, 1.0, v114
	v_add_f32_e32 v115, 1.0, v115
	v_add_f32_e32 v116, 1.0, v116
	v_add_f32_e32 v117, 1.0, v117
	v_add_f32_e32 v118, 1.0, v118
	v_add_f32_e32 v119, 1.0, v119
	v_mul_f32_e32 v156, v68, v104
	v_mul_f32_e32 v157, v69, v105
	v_mul_f32_e32 v158, v70, v106
	v_mul_f32_e32 v159, v71, v107
	v_mul_f32_e32 v160, v72, v108
	v_mul_f32_e32 v161, v73, v109
	v_mul_f32_e32 v162, v74, v110
	v_mul_f32_e32 v163, v75, v111
	v_mul_f32_e32 v164, v76, v112
	v_mul_f32_e32 v165, v77, v113
	v_mul_f32_e32 v166, v78, v114
	v_mul_f32_e32 v167, v79, v115
	v_mul_f32_e32 v168, v100, v116
	v_mul_f32_e32 v169, v101, v117
	v_mul_f32_e32 v170, v102, v118
	v_mul_f32_e32 v171, v103, v119

.Lrp10_go1:
	v_lshlrev_b32_e32 v100, 16, v228
	v_and_b32_e32 v101, 0xffff0000, v228
	v_lshlrev_b32_e32 v102, 16, v229
	v_and_b32_e32 v103, 0xffff0000, v229
	v_lshlrev_b32_e32 v104, 16, v230
	v_and_b32_e32 v105, 0xffff0000, v230
	v_lshlrev_b32_e32 v106, 16, v231
	v_and_b32_e32 v107, 0xffff0000, v231
	v_lshlrev_b32_e32 v108, 16, v232
	v_and_b32_e32 v109, 0xffff0000, v232
	v_lshlrev_b32_e32 v110, 16, v233
	v_and_b32_e32 v111, 0xffff0000, v233
	v_lshlrev_b32_e32 v112, 16, v234
	v_and_b32_e32 v113, 0xffff0000, v234
	v_lshlrev_b32_e32 v114, 16, v235
	v_and_b32_e32 v115, 0xffff0000, v235
	v_mul_f32_e32 v132, v100, v100
	v_mul_f32_e32 v133, v101, v101
	v_fmac_f32_e32 v132, v102, v102
	v_fmac_f32_e32 v133, v103, v103
	v_fmac_f32_e32 v132, v104, v104
	v_fmac_f32_e32 v133, v105, v105
	v_fmac_f32_e32 v132, v106, v106
	v_fmac_f32_e32 v133, v107, v107
	v_fmac_f32_e32 v132, v108, v108
	v_fmac_f32_e32 v133, v109, v109
	v_fmac_f32_e32 v132, v110, v110
	v_fmac_f32_e32 v133, v111, v111
	v_fmac_f32_e32 v132, v112, v112
	v_fmac_f32_e32 v133, v113, v113
	v_fmac_f32_e32 v132, v114, v114
	v_fmac_f32_e32 v133, v115, v115
	v_add_f32_e32 v132, v132, v133
	s_nop 1
	v_add_f32_dpp v132, v132, v132 quad_perm:[1,0,3,2] row_mask:0xf bank_mask:0xf bound_ctrl:1
	s_nop 1
	v_add_f32_dpp v132, v132, v132 quad_perm:[2,3,0,1] row_mask:0xf bank_mask:0xf bound_ctrl:1
	s_nop 1
	v_add_f32_dpp v132, v132, v132 row_ror:4 row_mask:0xf bank_mask:0xf bound_ctrl:1
	s_nop 1
	v_add_f32_dpp v132, v132, v132 row_ror:8 row_mask:0xf bank_mask:0xf bound_ctrl:1
	s_nop 1
	v_readlane_b32 s9, v132, 0
	v_readlane_b32 s38, v132, 16
	v_readlane_b32 s39, v132, 32
	v_readlane_b32 s40, v132, 48
	s_nop 2
	v_mov_b32_e32 v132, s9
	v_add_f32_e32 v132, s38, v132
	v_mov_b32_e32 v135, s39
	v_add_f32_e32 v135, s40, v135
	v_add_f32_e32 v132, v132, v135
	v_fmamk_f32 v132, v132, 0x3a800000, v238
	v_rsq_f32_e32 v132, v132
	s_nop 0
	v_mul_f32_e32 v100, v100, v132
	v_mul_f32_e32 v101, v101, v132
	v_mul_f32_e32 v102, v102, v132
	v_mul_f32_e32 v103, v103, v132
	v_mul_f32_e32 v104, v104, v132
	v_mul_f32_e32 v105, v105, v132
	v_mul_f32_e32 v106, v106, v132
	v_mul_f32_e32 v107, v107, v132
	v_mul_f32_e32 v108, v108, v132
	v_mul_f32_e32 v109, v109, v132
	v_mul_f32_e32 v110, v110, v132
	v_mul_f32_e32 v111, v111, v132
	v_mul_f32_e32 v112, v112, v132
	v_mul_f32_e32 v113, v113, v132
	v_mul_f32_e32 v114, v114, v132
	v_mul_f32_e32 v115, v115, v132
	v_fmac_f32_e32 v212, v140, v100
	v_fmac_f32_e32 v213, v141, v101
	v_fmac_f32_e32 v214, v142, v102
	v_fmac_f32_e32 v215, v143, v103
	v_fmac_f32_e32 v216, v144, v104
	v_fmac_f32_e32 v217, v145, v105
	v_fmac_f32_e32 v218, v146, v106
	v_fmac_f32_e32 v219, v147, v107
	v_fmac_f32_e32 v220, v148, v108
	v_fmac_f32_e32 v221, v149, v109
	v_fmac_f32_e32 v222, v150, v110
	v_fmac_f32_e32 v223, v151, v111
	v_fmac_f32_e32 v224, v152, v112
	v_fmac_f32_e32 v225, v153, v113
	v_fmac_f32_e32 v226, v154, v114
	v_fmac_f32_e32 v227, v155, v115
	global_store_dwordx4 v236, v[212:215], s[32:33] offset:0 nt
	global_store_dwordx4 v236, v[216:219], s[32:33] offset:1024 nt
	global_store_dwordx4 v236, v[220:223], s[32:33] offset:2048 nt
	global_store_dwordx4 v236, v[224:227], s[32:33] offset:3072 nt
	v_mul_f32_e32 v132, v212, v212
	v_mul_f32_e32 v133, v213, v213
	v_fmac_f32_e32 v132, v214, v214
	v_fmac_f32_e32 v133, v215, v215
	v_fmac_f32_e32 v132, v216, v216
	v_fmac_f32_e32 v133, v217, v217
	v_fmac_f32_e32 v132, v218, v218
	v_fmac_f32_e32 v133, v219, v219
	v_fmac_f32_e32 v132, v220, v220
	v_fmac_f32_e32 v133, v221, v221
	v_fmac_f32_e32 v132, v222, v222
	v_fmac_f32_e32 v133, v223, v223
	v_fmac_f32_e32 v132, v224, v224
	v_fmac_f32_e32 v133, v225, v225
	v_fmac_f32_e32 v132, v226, v226
	v_fmac_f32_e32 v133, v227, v227
	v_add_f32_e32 v132, v132, v133
	s_nop 1
	v_add_f32_dpp v132, v132, v132 quad_perm:[1,0,3,2] row_mask:0xf bank_mask:0xf bound_ctrl:1
	s_nop 1
	v_add_f32_dpp v132, v132, v132 quad_perm:[2,3,0,1] row_mask:0xf bank_mask:0xf bound_ctrl:1
	s_nop 1
	v_add_f32_dpp v132, v132, v132 row_ror:4 row_mask:0xf bank_mask:0xf bound_ctrl:1
	s_nop 1
	v_add_f32_dpp v132, v132, v132 row_ror:8 row_mask:0xf bank_mask:0xf bound_ctrl:1
	s_nop 1
	v_readlane_b32 s9, v132, 0
	v_readlane_b32 s38, v132, 16
	v_readlane_b32 s39, v132, 32
	v_readlane_b32 s40, v132, 48
	s_nop 2
	v_mov_b32_e32 v132, s9
	v_add_f32_e32 v132, s38, v132
	v_mov_b32_e32 v135, s39
	v_add_f32_e32 v135, s40, v135
	v_add_f32_e32 v132, v132, v135
	v_fmamk_f32 v132, v132, 0x3a800000, v238
	v_rsq_f32_e32 v132, v132
	s_nop 0
	v_mul_f32_e32 v116, v212, v132
	v_mul_f32_e32 v117, v213, v132
	v_mul_f32_e32 v118, v214, v132
	v_mul_f32_e32 v119, v215, v132
	v_mul_f32_e32 v120, v216, v132
	v_mul_f32_e32 v121, v217, v132
	v_mul_f32_e32 v122, v218, v132
	v_mul_f32_e32 v123, v219, v132
	v_mul_f32_e32 v124, v220, v132
	v_mul_f32_e32 v125, v221, v132
	v_mul_f32_e32 v126, v222, v132
	v_mul_f32_e32 v127, v223, v132
	v_mul_f32_e32 v128, v224, v132
	v_mul_f32_e32 v129, v225, v132
	v_mul_f32_e32 v130, v226, v132
	v_mul_f32_e32 v131, v227, v132
	v_fma_f32 v116, v116, v156, v172
	v_fma_f32 v117, v117, v157, v173
	v_fma_f32 v118, v118, v158, v174
	v_fma_f32 v119, v119, v159, v175
	v_fma_f32 v120, v120, v160, v176
	v_fma_f32 v121, v121, v161, v177
	v_fma_f32 v122, v122, v162, v178
	v_fma_f32 v123, v123, v163, v179
	v_fma_f32 v124, v124, v164, v180
	v_fma_f32 v125, v125, v165, v181
	v_fma_f32 v126, v126, v166, v182
	v_fma_f32 v127, v127, v167, v183
	v_fma_f32 v128, v128, v168, v184
	v_fma_f32 v129, v129, v169, v185
	v_fma_f32 v130, v130, v170, v186
	v_fma_f32 v131, v131, v171, v187
	v_cvt_pk_bf16_f32 v116, v116, v117
	v_cvt_pk_bf16_f32 v117, v118, v119
	v_cvt_pk_bf16_f32 v118, v120, v121
	v_cvt_pk_bf16_f32 v119, v122, v123
	v_cvt_pk_bf16_f32 v120, v124, v125
	v_cvt_pk_bf16_f32 v121, v126, v127
	v_cvt_pk_bf16_f32 v122, v128, v129
	v_cvt_pk_bf16_f32 v123, v130, v131
	global_store_dwordx2 v237, v[116:117], s[34:35] offset:0
	global_store_dwordx2 v237, v[118:119], s[34:35] offset:512
	global_store_dwordx2 v237, v[120:121], s[34:35] offset:1024
	global_store_dwordx2 v237, v[122:123], s[34:35] offset:1536
	s_cmp_lt_u32 s6, s7
	s_cbranch_scc1 .Lrp10_loop

.Lrp20_go0:
	v_lshlrev_b32_e32 v100, 16, v204
	v_and_b32_e32 v101, 0xffff0000, v204
	v_lshlrev_b32_e32 v102, 16, v205
	v_and_b32_e32 v103, 0xffff0000, v205
	v_lshlrev_b32_e32 v104, 16, v206
	v_and_b32_e32 v105, 0xffff0000, v206
	v_lshlrev_b32_e32 v106, 16, v207
	v_and_b32_e32 v107, 0xffff0000, v207
	v_lshlrev_b32_e32 v108, 16, v208
	v_and_b32_e32 v109, 0xffff0000, v208
	v_lshlrev_b32_e32 v110, 16, v209
	v_and_b32_e32 v111, 0xffff0000, v209
	v_lshlrev_b32_e32 v112, 16, v210
	v_and_b32_e32 v113, 0xffff0000, v210
	v_lshlrev_b32_e32 v114, 16, v211
	v_and_b32_e32 v115, 0xffff0000, v211
	v_mul_f32_e32 v132, v100, v100
	v_mul_f32_e32 v133, v101, v101
	v_fmac_f32_e32 v132, v102, v102
	v_fmac_f32_e32 v133, v103, v103
	v_fmac_f32_e32 v132, v104, v104
	v_fmac_f32_e32 v133, v105, v105
	v_fmac_f32_e32 v132, v106, v106
	v_fmac_f32_e32 v133, v107, v107
	v_fmac_f32_e32 v132, v108, v108
	v_fmac_f32_e32 v133, v109, v109
	v_fmac_f32_e32 v132, v110, v110
	v_fmac_f32_e32 v133, v111, v111
	v_fmac_f32_e32 v132, v112, v112
	v_fmac_f32_e32 v133, v113, v113
	v_fmac_f32_e32 v132, v114, v114
	v_fmac_f32_e32 v133, v115, v115
	v_add_f32_e32 v132, v132, v133
	s_nop 1
	v_add_f32_dpp v132, v132, v132 quad_perm:[1,0,3,2] row_mask:0xf bank_mask:0xf bound_ctrl:1
	s_nop 1
	v_add_f32_dpp v132, v132, v132 quad_perm:[2,3,0,1] row_mask:0xf bank_mask:0xf bound_ctrl:1
	s_nop 1
	v_add_f32_dpp v132, v132, v132 row_ror:4 row_mask:0xf bank_mask:0xf bound_ctrl:1
	s_nop 1
	v_add_f32_dpp v132, v132, v132 row_ror:8 row_mask:0xf bank_mask:0xf bound_ctrl:1
	s_nop 1
	v_readlane_b32 s9, v132, 0
	v_readlane_b32 s38, v132, 16
	v_readlane_b32 s39, v132, 32
	v_readlane_b32 s40, v132, 48
	s_nop 2
	v_mov_b32_e32 v132, s9
	v_add_f32_e32 v132, s38, v132
	v_mov_b32_e32 v135, s39
	v_add_f32_e32 v135, s40, v135
	v_add_f32_e32 v132, v132, v135
	v_fmamk_f32 v132, v132, 0x3a800000, v238
	v_rsq_f32_e32 v132, v132
	s_nop 0
	v_mul_f32_e32 v100, v100, v132
	v_mul_f32_e32 v101, v101, v132
	v_mul_f32_e32 v102, v102, v132
	v_mul_f32_e32 v103, v103, v132
	v_mul_f32_e32 v104, v104, v132
	v_mul_f32_e32 v105, v105, v132
	v_mul_f32_e32 v106, v106, v132
	v_mul_f32_e32 v107, v107, v132
	v_mul_f32_e32 v108, v108, v132
	v_mul_f32_e32 v109, v109, v132
	v_mul_f32_e32 v110, v110, v132
	v_mul_f32_e32 v111, v111, v132
	v_mul_f32_e32 v112, v112, v132
	v_mul_f32_e32 v113, v113, v132
	v_mul_f32_e32 v114, v114, v132
	v_mul_f32_e32 v115, v115, v132
	v_fmac_f32_e32 v188, v140, v100
	v_fmac_f32_e32 v189, v141, v101
	v_fmac_f32_e32 v190, v142, v102
	v_fmac_f32_e32 v191, v143, v103
	v_fmac_f32_e32 v192, v144, v104
	v_fmac_f32_e32 v193, v145, v105
	v_fmac_f32_e32 v194, v146, v106
	v_fmac_f32_e32 v195, v147, v107
	v_fmac_f32_e32 v196, v148, v108
	v_fmac_f32_e32 v197, v149, v109
	v_fmac_f32_e32 v198, v150, v110
	v_fmac_f32_e32 v199, v151, v111
	v_fmac_f32_e32 v200, v152, v112
	v_fmac_f32_e32 v201, v153, v113
	v_fmac_f32_e32 v202, v154, v114
	v_fmac_f32_e32 v203, v155, v115
	global_store_dwordx4 v236, v[188:191], s[32:33] offset:0 nt
	global_store_dwordx4 v236, v[192:195], s[32:33] offset:1024 nt
	global_store_dwordx4 v236, v[196:199], s[32:33] offset:2048 nt
	global_store_dwordx4 v236, v[200:203], s[32:33] offset:3072 nt
	v_mul_f32_e32 v132, v188, v188
	v_mul_f32_e32 v133, v189, v189
	v_fmac_f32_e32 v132, v190, v190
	v_fmac_f32_e32 v133, v191, v191
	v_fmac_f32_e32 v132, v192, v192
	v_fmac_f32_e32 v133, v193, v193
	v_fmac_f32_e32 v132, v194, v194
	v_fmac_f32_e32 v133, v195, v195
	v_fmac_f32_e32 v132, v196, v196
	v_fmac_f32_e32 v133, v197, v197
	v_fmac_f32_e32 v132, v198, v198
	v_fmac_f32_e32 v133, v199, v199
	v_fmac_f32_e32 v132, v200, v200
	v_fmac_f32_e32 v133, v201, v201
	v_fmac_f32_e32 v132, v202, v202
	v_fmac_f32_e32 v133, v203, v203
	v_add_f32_e32 v132, v132, v133
	s_nop 1
	v_add_f32_dpp v132, v132, v132 quad_perm:[1,0,3,2] row_mask:0xf bank_mask:0xf bound_ctrl:1
	s_nop 1
	v_add_f32_dpp v132, v132, v132 quad_perm:[2,3,0,1] row_mask:0xf bank_mask:0xf bound_ctrl:1
	s_nop 1
	v_add_f32_dpp v132, v132, v132 row_ror:4 row_mask:0xf bank_mask:0xf bound_ctrl:1
	s_nop 1
	v_add_f32_dpp v132, v132, v132 row_ror:8 row_mask:0xf bank_mask:0xf bound_ctrl:1
	s_nop 1
	v_readlane_b32 s9, v132, 0
	v_readlane_b32 s38, v132, 16
	v_readlane_b32 s39, v132, 32
	v_readlane_b32 s40, v132, 48
	s_nop 2
	v_mov_b32_e32 v132, s9
	v_add_f32_e32 v132, s38, v132
	v_mov_b32_e32 v135, s39
	v_add_f32_e32 v135, s40, v135
	v_add_f32_e32 v132, v132, v135
	v_fmamk_f32 v132, v132, 0x3a800000, v238
	v_rsq_f32_e32 v132, v132
	s_nop 0
	v_mul_f32_e32 v116, v188, v132
	v_mul_f32_e32 v117, v189, v132
	v_mul_f32_e32 v118, v190, v132
	v_mul_f32_e32 v119, v191, v132
	v_mul_f32_e32 v120, v192, v132
	v_mul_f32_e32 v121, v193, v132
	v_mul_f32_e32 v122, v194, v132
	v_mul_f32_e32 v123, v195, v132
	v_mul_f32_e32 v124, v196, v132
	v_mul_f32_e32 v125, v197, v132
	v_mul_f32_e32 v126, v198, v132
	v_mul_f32_e32 v127, v199, v132
	v_mul_f32_e32 v128, v200, v132
	v_mul_f32_e32 v129, v201, v132
	v_mul_f32_e32 v130, v202, v132
	v_mul_f32_e32 v131, v203, v132
	v_fma_f32 v116, v116, v156, v172
	v_fma_f32 v117, v117, v157, v173
	v_fma_f32 v118, v118, v158, v174
	v_fma_f32 v119, v119, v159, v175
	v_fma_f32 v120, v120, v160, v176
	v_fma_f32 v121, v121, v161, v177
	v_fma_f32 v122, v122, v162, v178
	v_fma_f32 v123, v123, v163, v179
	v_fma_f32 v124, v124, v164, v180
	v_fma_f32 v125, v125, v165, v181
	v_fma_f32 v126, v126, v166, v182
	v_fma_f32 v127, v127, v167, v183
	v_fma_f32 v128, v128, v168, v184
	v_fma_f32 v129, v129, v169, v185
	v_fma_f32 v130, v130, v170, v186
	v_fma_f32 v131, v131, v171, v187
	v_cvt_pk_bf16_f32 v116, v116, v117
	v_cvt_pk_bf16_f32 v117, v118, v119
	v_cvt_pk_bf16_f32 v118, v120, v121
	v_cvt_pk_bf16_f32 v119, v122, v123
	v_cvt_pk_bf16_f32 v120, v124, v125
	v_cvt_pk_bf16_f32 v121, v126, v127
	v_cvt_pk_bf16_f32 v122, v128, v129
	v_cvt_pk_bf16_f32 v123, v130, v131
	global_store_dwordx2 v237, v[116:117], s[34:35] offset:0
	global_store_dwordx2 v237, v[118:119], s[34:35] offset:512
	global_store_dwordx2 v237, v[120:121], s[34:35] offset:1024
	global_store_dwordx2 v237, v[122:123], s[34:35] offset:1536
	s_cmp_lt_u32 s6, s7
	s_cbranch_scc0 .Lrp20_done
	s_sub_u32 s9, s6, 0x2000
	s_ashr_i32 s9, s9, 10
	s_add_i32 s9, s9, 1
	s_max_i32 s9, s9, 0
	s_cmp_eq_u32 s9, s8
	s_cbranch_scc1 .Lrp20_same1
	s_mov_b32 s8, s9
	s_add_i32 s9, s8, 0
	s_mul_i32 s9, s9, 0x6000
	s_add_u32 s36, s22, s9
	s_addc_u32 s37, s23, 0
	s_add_u32 s38, s36, 0x5000
	s_addc_u32 s39, s37, 0
	global_load_dwordx4 v[32:35], v236, s[38:39] offset:0
	global_load_dwordx4 v[36:39], v236, s[38:39] offset:1024
	global_load_dwordx4 v[40:43], v236, s[38:39] offset:2048
	global_load_dwordx4 v[44:47], v236, s[38:39] offset:3072
	global_load_dwordx4 v[48:51], v236, s[10:11] offset:0
	global_load_dwordx4 v[52:55], v236, s[10:11] offset:1024
	global_load_dwordx4 v[56:59], v236, s[10:11] offset:2048
	global_load_dwordx4 v[64:67], v236, s[10:11] offset:3072
	s_add_i32 s9, s8, 3
	s_mul_i32 s9, s9, 0x6000
	s_add_u32 s36, s22, s9
	s_addc_u32 s37, s23, 0
	global_load_dwordx4 v[68:71], v236, s[12:13] offset:0
	global_load_dwordx4 v[72:75], v236, s[12:13] offset:1024
	global_load_dwordx4 v[76:79], v236, s[12:13] offset:2048
	global_load_dwordx4 v[100:103], v236, s[12:13] offset:3072
	s_add_u32 s38, s36, 0x1000
	s_addc_u32 s39, s37, 0
	global_load_dwordx4 v[104:107], v236, s[38:39] offset:0
	global_load_dwordx4 v[108:111], v236, s[38:39] offset:1024
	global_load_dwordx4 v[112:115], v236, s[38:39] offset:2048
	global_load_dwordx4 v[116:119], v236, s[38:39] offset:3072
	s_add_u32 s38, s36, 0x0
	s_addc_u32 s39, s37, 0
	global_load_dwordx4 v[172:175], v236, s[38:39] offset:0
	global_load_dwordx4 v[176:179], v236, s[38:39] offset:1024
	global_load_dwordx4 v[180:183], v236, s[38:39] offset:2048
	global_load_dwordx4 v[184:187], v236, s[38:39] offset:3072
	s_waitcnt vmcnt(0)
	v_mul_f32_e32 v140, v32, v48
	v_mul_f32_e32 v141, v33, v49
	v_mul_f32_e32 v142, v34, v50
	v_mul_f32_e32 v143, v35, v51
	v_mul_f32_e32 v144, v36, v52
	v_mul_f32_e32 v145, v37, v53
	v_mul_f32_e32 v146, v38, v54
	v_mul_f32_e32 v147, v39, v55
	v_mul_f32_e32 v148, v40, v56
	v_mul_f32_e32 v149, v41, v57
	v_mul_f32_e32 v150, v42, v58
	v_mul_f32_e32 v151, v43, v59
	v_mul_f32_e32 v152, v44, v64
	v_mul_f32_e32 v153, v45, v65
	v_mul_f32_e32 v154, v46, v66
	v_mul_f32_e32 v155, v47, v67
	v_add_f32_e32 v104, 1.0, v104
	v_add_f32_e32 v105, 1.0, v105
	v_add_f32_e32 v106, 1.0, v106
	v_add_f32_e32 v107, 1.0, v107
	v_add_f32_e32 v108, 1.0, v108
	v_add_f32_e32 v109, 1.0, v109
	v_add_f32_e32 v110, 1.0, v110
	v_add_f32_e32 v111, 1.0, v111
	v_add_f32_e32 v112, 1.0, v112
	v_add_f32_e32 v113, 1.0, v113
	v_add_f32_e32 v114, 1.0, v114
	v_add_f32_e32 v115, 1.0, v115
	v_add_f32_e32 v116, 1.0, v116
	v_add_f32_e32 v117, 1.0, v117
	v_add_f32_e32 v118, 1.0, v118
	v_add_f32_e32 v119, 1.0, v119
	v_mul_f32_e32 v156, v68, v104
	v_mul_f32_e32 v157, v69, v105
	v_mul_f32_e32 v158, v70, v106
	v_mul_f32_e32 v159, v71, v107
	v_mul_f32_e32 v160, v72, v108
	v_mul_f32_e32 v161, v73, v109
	v_mul_f32_e32 v162, v74, v110
	v_mul_f32_e32 v163, v75, v111
	v_mul_f32_e32 v164, v76, v112
	v_mul_f32_e32 v165, v77, v113
	v_mul_f32_e32 v166, v78, v114
	v_mul_f32_e32 v167, v79, v115
	v_mul_f32_e32 v168, v100, v116
	v_mul_f32_e32 v169, v101, v117
	v_mul_f32_e32 v170, v102, v118
	v_mul_f32_e32 v171, v103, v119

.Lrp11_go0:
	v_lshlrev_b32_e32 v100, 16, v204
	v_and_b32_e32 v101, 0xffff0000, v204
	v_lshlrev_b32_e32 v102, 16, v205
	v_and_b32_e32 v103, 0xffff0000, v205
	v_lshlrev_b32_e32 v104, 16, v206
	v_and_b32_e32 v105, 0xffff0000, v206
	v_lshlrev_b32_e32 v106, 16, v207
	v_and_b32_e32 v107, 0xffff0000, v207
	v_lshlrev_b32_e32 v108, 16, v208
	v_and_b32_e32 v109, 0xffff0000, v208
	v_lshlrev_b32_e32 v110, 16, v209
	v_and_b32_e32 v111, 0xffff0000, v209
	v_lshlrev_b32_e32 v112, 16, v210
	v_and_b32_e32 v113, 0xffff0000, v210
	v_lshlrev_b32_e32 v114, 16, v211
	v_and_b32_e32 v115, 0xffff0000, v211
	v_mul_f32_e32 v132, v100, v100
	v_mul_f32_e32 v133, v101, v101
	v_fmac_f32_e32 v132, v102, v102
	v_fmac_f32_e32 v133, v103, v103
	v_fmac_f32_e32 v132, v104, v104
	v_fmac_f32_e32 v133, v105, v105
	v_fmac_f32_e32 v132, v106, v106
	v_fmac_f32_e32 v133, v107, v107
	v_fmac_f32_e32 v132, v108, v108
	v_fmac_f32_e32 v133, v109, v109
	v_fmac_f32_e32 v132, v110, v110
	v_fmac_f32_e32 v133, v111, v111
	v_fmac_f32_e32 v132, v112, v112
	v_fmac_f32_e32 v133, v113, v113
	v_fmac_f32_e32 v132, v114, v114
	v_fmac_f32_e32 v133, v115, v115
	v_add_f32_e32 v132, v132, v133
	s_nop 1
	v_add_f32_dpp v132, v132, v132 quad_perm:[1,0,3,2] row_mask:0xf bank_mask:0xf bound_ctrl:1
	s_nop 1
	v_add_f32_dpp v132, v132, v132 quad_perm:[2,3,0,1] row_mask:0xf bank_mask:0xf bound_ctrl:1
	s_nop 1
	v_add_f32_dpp v132, v132, v132 row_ror:4 row_mask:0xf bank_mask:0xf bound_ctrl:1
	s_nop 1
	v_add_f32_dpp v132, v132, v132 row_ror:8 row_mask:0xf bank_mask:0xf bound_ctrl:1
	s_nop 1
	v_readlane_b32 s9, v132, 0
	v_readlane_b32 s38, v132, 16
	v_readlane_b32 s39, v132, 32
	v_readlane_b32 s40, v132, 48
	s_nop 2
	v_mov_b32_e32 v132, s9
	v_add_f32_e32 v132, s38, v132
	v_mov_b32_e32 v135, s39
	v_add_f32_e32 v135, s40, v135
	v_add_f32_e32 v132, v132, v135
	v_fmamk_f32 v132, v132, 0x3a800000, v238
	v_rsq_f32_e32 v132, v132
	s_nop 0
	v_mul_f32_e32 v100, v100, v132
	v_mul_f32_e32 v101, v101, v132
	v_mul_f32_e32 v102, v102, v132
	v_mul_f32_e32 v103, v103, v132
	v_mul_f32_e32 v104, v104, v132
	v_mul_f32_e32 v105, v105, v132
	v_mul_f32_e32 v106, v106, v132
	v_mul_f32_e32 v107, v107, v132
	v_mul_f32_e32 v108, v108, v132
	v_mul_f32_e32 v109, v109, v132
	v_mul_f32_e32 v110, v110, v132
	v_mul_f32_e32 v111, v111, v132
	v_mul_f32_e32 v112, v112, v132
	v_mul_f32_e32 v113, v113, v132
	v_mul_f32_e32 v114, v114, v132
	v_mul_f32_e32 v115, v115, v132
	v_fmac_f32_e32 v188, v140, v100
	v_fmac_f32_e32 v189, v141, v101
	v_fmac_f32_e32 v190, v142, v102
	v_fmac_f32_e32 v191, v143, v103
	v_fmac_f32_e32 v192, v144, v104
	v_fmac_f32_e32 v193, v145, v105
	v_fmac_f32_e32 v194, v146, v106
	v_fmac_f32_e32 v195, v147, v107
	v_fmac_f32_e32 v196, v148, v108
	v_fmac_f32_e32 v197, v149, v109
	v_fmac_f32_e32 v198, v150, v110
	v_fmac_f32_e32 v199, v151, v111
	v_fmac_f32_e32 v200, v152, v112
	v_fmac_f32_e32 v201, v153, v113
	v_fmac_f32_e32 v202, v154, v114
	v_fmac_f32_e32 v203, v155, v115
	global_store_dwordx4 v236, v[188:191], s[32:33] offset:0 nt
	global_store_dwordx4 v236, v[192:195], s[32:33] offset:1024 nt
	global_store_dwordx4 v236, v[196:199], s[32:33] offset:2048 nt
	global_store_dwordx4 v236, v[200:203], s[32:33] offset:3072 nt
	v_mul_f32_e32 v132, v188, v188
	v_mul_f32_e32 v133, v189, v189
	v_fmac_f32_e32 v132, v190, v190
	v_fmac_f32_e32 v133, v191, v191
	v_fmac_f32_e32 v132, v192, v192
	v_fmac_f32_e32 v133, v193, v193
	v_fmac_f32_e32 v132, v194, v194
	v_fmac_f32_e32 v133, v195, v195
	v_fmac_f32_e32 v132, v196, v196
	v_fmac_f32_e32 v133, v197, v197
	v_fmac_f32_e32 v132, v198, v198
	v_fmac_f32_e32 v133, v199, v199
	v_fmac_f32_e32 v132, v200, v200
	v_fmac_f32_e32 v133, v201, v201
	v_fmac_f32_e32 v132, v202, v202
	v_fmac_f32_e32 v133, v203, v203
	v_add_f32_e32 v132, v132, v133
	s_nop 1
	v_add_f32_dpp v132, v132, v132 quad_perm:[1,0,3,2] row_mask:0xf bank_mask:0xf bound_ctrl:1
	s_nop 1
	v_add_f32_dpp v132, v132, v132 quad_perm:[2,3,0,1] row_mask:0xf bank_mask:0xf bound_ctrl:1
	s_nop 1
	v_add_f32_dpp v132, v132, v132 row_ror:4 row_mask:0xf bank_mask:0xf bound_ctrl:1
	s_nop 1
	v_add_f32_dpp v132, v132, v132 row_ror:8 row_mask:0xf bank_mask:0xf bound_ctrl:1
	s_nop 1
	v_readlane_b32 s9, v132, 0
	v_readlane_b32 s38, v132, 16
	v_readlane_b32 s39, v132, 32
	v_readlane_b32 s40, v132, 48
	s_nop 2
	v_mov_b32_e32 v132, s9
	v_add_f32_e32 v132, s38, v132
	v_mov_b32_e32 v135, s39
	v_add_f32_e32 v135, s40, v135
	v_add_f32_e32 v132, v132, v135
	v_fmamk_f32 v132, v132, 0x3a800000, v238
	v_rsq_f32_e32 v132, v132
	s_nop 0
	v_mul_f32_e32 v116, v188, v132
	v_mul_f32_e32 v117, v189, v132
	v_mul_f32_e32 v118, v190, v132
	v_mul_f32_e32 v119, v191, v132
	v_mul_f32_e32 v120, v192, v132
	v_mul_f32_e32 v121, v193, v132
	v_mul_f32_e32 v122, v194, v132
	v_mul_f32_e32 v123, v195, v132
	v_mul_f32_e32 v124, v196, v132
	v_mul_f32_e32 v125, v197, v132
	v_mul_f32_e32 v126, v198, v132
	v_mul_f32_e32 v127, v199, v132
	v_mul_f32_e32 v128, v200, v132
	v_mul_f32_e32 v129, v201, v132
	v_mul_f32_e32 v130, v202, v132
	v_mul_f32_e32 v131, v203, v132
	v_fma_f32 v116, v116, v156, v172
	v_fma_f32 v117, v117, v157, v173
	v_fma_f32 v118, v118, v158, v174
	v_fma_f32 v119, v119, v159, v175
	v_fma_f32 v120, v120, v160, v176
	v_fma_f32 v121, v121, v161, v177
	v_fma_f32 v122, v122, v162, v178
	v_fma_f32 v123, v123, v163, v179
	v_fma_f32 v124, v124, v164, v180
	v_fma_f32 v125, v125, v165, v181
	v_fma_f32 v126, v126, v166, v182
	v_fma_f32 v127, v127, v167, v183
	v_fma_f32 v128, v128, v168, v184
	v_fma_f32 v129, v129, v169, v185
	v_fma_f32 v130, v130, v170, v186
	v_fma_f32 v131, v131, v171, v187
	v_cvt_pk_bf16_f32 v116, v116, v117
	v_cvt_pk_bf16_f32 v117, v118, v119
	v_cvt_pk_bf16_f32 v118, v120, v121
	v_cvt_pk_bf16_f32 v119, v122, v123
	v_cvt_pk_bf16_f32 v120, v124, v125
	v_cvt_pk_bf16_f32 v121, v126, v127
	v_cvt_pk_bf16_f32 v122, v128, v129
	v_cvt_pk_bf16_f32 v123, v130, v131
	global_store_dwordx2 v237, v[116:117], s[34:35] offset:0
	global_store_dwordx2 v237, v[118:119], s[34:35] offset:512
	global_store_dwordx2 v237, v[120:121], s[34:35] offset:1024
	global_store_dwordx2 v237, v[122:123], s[34:35] offset:1536
	s_cmp_lt_u32 s6, s7
	s_cbranch_scc0 .Lrp11_done
	s_sub_u32 s9, s6, 0x2000
	s_ashr_i32 s9, s9, 10
	s_add_i32 s9, s9, 1
	s_max_i32 s9, s9, 0
	s_cmp_eq_u32 s9, s8
	s_cbranch_scc1 .Lrp11_same1
	s_mov_b32 s8, s9
	s_add_i32 s9, s8, 3
	s_mul_i32 s9, s9, 0x6000
	s_add_u32 s36, s22, s9
	s_addc_u32 s37, s23, 0
	s_add_u32 s38, s36, 0x2000
	s_addc_u32 s39, s37, 0
	global_load_dwordx4 v[32:35], v236, s[38:39] offset:0
	global_load_dwordx4 v[36:39], v236, s[38:39] offset:1024
	global_load_dwordx4 v[40:43], v236, s[38:39] offset:2048
	global_load_dwordx4 v[44:47], v236, s[38:39] offset:3072
	global_load_dwordx4 v[48:51], v236, s[10:11] offset:0
	global_load_dwordx4 v[52:55], v236, s[10:11] offset:1024
	global_load_dwordx4 v[56:59], v236, s[10:11] offset:2048
	global_load_dwordx4 v[64:67], v236, s[10:11] offset:3072
	global_load_dwordx4 v[68:71], v236, s[12:13] offset:0
	global_load_dwordx4 v[72:75], v236, s[12:13] offset:1024
	global_load_dwordx4 v[76:79], v236, s[12:13] offset:2048
	global_load_dwordx4 v[100:103], v236, s[12:13] offset:3072
	s_add_u32 s38, s36, 0x4000
	s_addc_u32 s39, s37, 0
	global_load_dwordx4 v[104:107], v236, s[38:39] offset:0
	global_load_dwordx4 v[108:111], v236, s[38:39] offset:1024
	global_load_dwordx4 v[112:115], v236, s[38:39] offset:2048
	global_load_dwordx4 v[116:119], v236, s[38:39] offset:3072
	s_add_u32 s38, s36, 0x3000
	s_addc_u32 s39, s37, 0
	global_load_dwordx4 v[172:175], v236, s[38:39] offset:0
	global_load_dwordx4 v[176:179], v236, s[38:39] offset:1024
	global_load_dwordx4 v[180:183], v236, s[38:39] offset:2048
	global_load_dwordx4 v[184:187], v236, s[38:39] offset:3072
	s_waitcnt vmcnt(0)
	v_mul_f32_e32 v140, v32, v48
	v_mul_f32_e32 v141, v33, v49
	v_mul_f32_e32 v142, v34, v50
	v_mul_f32_e32 v143, v35, v51
	v_mul_f32_e32 v144, v36, v52
	v_mul_f32_e32 v145, v37, v53
	v_mul_f32_e32 v146, v38, v54
	v_mul_f32_e32 v147, v39, v55
	v_mul_f32_e32 v148, v40, v56
	v_mul_f32_e32 v149, v41, v57
	v_mul_f32_e32 v150, v42, v58
	v_mul_f32_e32 v151, v43, v59
	v_mul_f32_e32 v152, v44, v64
	v_mul_f32_e32 v153, v45, v65
	v_mul_f32_e32 v154, v46, v66
	v_mul_f32_e32 v155, v47, v67
	v_add_f32_e32 v104, 1.0, v104
	v_add_f32_e32 v105, 1.0, v105
	v_add_f32_e32 v106, 1.0, v106
	v_add_f32_e32 v107, 1.0, v107
	v_add_f32_e32 v108, 1.0, v108
	v_add_f32_e32 v109, 1.0, v109
	v_add_f32_e32 v110, 1.0, v110
	v_add_f32_e32 v111, 1.0, v111
	v_add_f32_e32 v112, 1.0, v112
	v_add_f32_e32 v113, 1.0, v113
	v_add_f32_e32 v114, 1.0, v114
	v_add_f32_e32 v115, 1.0, v115
	v_add_f32_e32 v116, 1.0, v116
	v_add_f32_e32 v117, 1.0, v117
	v_add_f32_e32 v118, 1.0, v118
	v_add_f32_e32 v119, 1.0, v119
	v_mul_f32_e32 v156, v68, v104
	v_mul_f32_e32 v157, v69, v105
	v_mul_f32_e32 v158, v70, v106
	v_mul_f32_e32 v159, v71, v107
	v_mul_f32_e32 v160, v72, v108
	v_mul_f32_e32 v161, v73, v109
	v_mul_f32_e32 v162, v74, v110
	v_mul_f32_e32 v163, v75, v111
	v_mul_f32_e32 v164, v76, v112
	v_mul_f32_e32 v165, v77, v113
	v_mul_f32_e32 v166, v78, v114
	v_mul_f32_e32 v167, v79, v115
	v_mul_f32_e32 v168, v100, v116
	v_mul_f32_e32 v169, v101, v117
	v_mul_f32_e32 v170, v102, v118
	v_mul_f32_e32 v171, v103, v119

.Lrp21_go0:
	v_lshlrev_b32_e32 v100, 16, v204
	v_and_b32_e32 v101, 0xffff0000, v204
	v_lshlrev_b32_e32 v102, 16, v205
	v_and_b32_e32 v103, 0xffff0000, v205
	v_lshlrev_b32_e32 v104, 16, v206
	v_and_b32_e32 v105, 0xffff0000, v206
	v_lshlrev_b32_e32 v106, 16, v207
	v_and_b32_e32 v107, 0xffff0000, v207
	v_lshlrev_b32_e32 v108, 16, v208
	v_and_b32_e32 v109, 0xffff0000, v208
	v_lshlrev_b32_e32 v110, 16, v209
	v_and_b32_e32 v111, 0xffff0000, v209
	v_lshlrev_b32_e32 v112, 16, v210
	v_and_b32_e32 v113, 0xffff0000, v210
	v_lshlrev_b32_e32 v114, 16, v211
	v_and_b32_e32 v115, 0xffff0000, v211
	v_mul_f32_e32 v132, v100, v100
	v_mul_f32_e32 v133, v101, v101
	v_fmac_f32_e32 v132, v102, v102
	v_fmac_f32_e32 v133, v103, v103
	v_fmac_f32_e32 v132, v104, v104
	v_fmac_f32_e32 v133, v105, v105
	v_fmac_f32_e32 v132, v106, v106
	v_fmac_f32_e32 v133, v107, v107
	v_fmac_f32_e32 v132, v108, v108
	v_fmac_f32_e32 v133, v109, v109
	v_fmac_f32_e32 v132, v110, v110
	v_fmac_f32_e32 v133, v111, v111
	v_fmac_f32_e32 v132, v112, v112
	v_fmac_f32_e32 v133, v113, v113
	v_fmac_f32_e32 v132, v114, v114
	v_fmac_f32_e32 v133, v115, v115
	v_add_f32_e32 v132, v132, v133
	s_nop 1
	v_add_f32_dpp v132, v132, v132 quad_perm:[1,0,3,2] row_mask:0xf bank_mask:0xf bound_ctrl:1
	s_nop 1
	v_add_f32_dpp v132, v132, v132 quad_perm:[2,3,0,1] row_mask:0xf bank_mask:0xf bound_ctrl:1
	s_nop 1
	v_add_f32_dpp v132, v132, v132 row_ror:4 row_mask:0xf bank_mask:0xf bound_ctrl:1
	s_nop 1
	v_add_f32_dpp v132, v132, v132 row_ror:8 row_mask:0xf bank_mask:0xf bound_ctrl:1
	s_nop 1
	v_readlane_b32 s9, v132, 0
	v_readlane_b32 s38, v132, 16
	v_readlane_b32 s39, v132, 32
	v_readlane_b32 s40, v132, 48
	s_nop 2
	v_mov_b32_e32 v132, s9
	v_add_f32_e32 v132, s38, v132
	v_mov_b32_e32 v135, s39
	v_add_f32_e32 v135, s40, v135
	v_add_f32_e32 v132, v132, v135
	v_fmamk_f32 v132, v132, 0x3a800000, v238
	v_rsq_f32_e32 v132, v132
	s_nop 0
	v_mul_f32_e32 v100, v100, v132
	v_mul_f32_e32 v101, v101, v132
	v_mul_f32_e32 v102, v102, v132
	v_mul_f32_e32 v103, v103, v132
	v_mul_f32_e32 v104, v104, v132
	v_mul_f32_e32 v105, v105, v132
	v_mul_f32_e32 v106, v106, v132
	v_mul_f32_e32 v107, v107, v132
	v_mul_f32_e32 v108, v108, v132
	v_mul_f32_e32 v109, v109, v132
	v_mul_f32_e32 v110, v110, v132
	v_mul_f32_e32 v111, v111, v132
	v_mul_f32_e32 v112, v112, v132
	v_mul_f32_e32 v113, v113, v132
	v_mul_f32_e32 v114, v114, v132
	v_mul_f32_e32 v115, v115, v132
	v_fmac_f32_e32 v188, v140, v100
	v_fmac_f32_e32 v189, v141, v101
	v_fmac_f32_e32 v190, v142, v102
	v_fmac_f32_e32 v191, v143, v103
	v_fmac_f32_e32 v192, v144, v104
	v_fmac_f32_e32 v193, v145, v105
	v_fmac_f32_e32 v194, v146, v106
	v_fmac_f32_e32 v195, v147, v107
	v_fmac_f32_e32 v196, v148, v108
	v_fmac_f32_e32 v197, v149, v109
	v_fmac_f32_e32 v198, v150, v110
	v_fmac_f32_e32 v199, v151, v111
	v_fmac_f32_e32 v200, v152, v112
	v_fmac_f32_e32 v201, v153, v113
	v_fmac_f32_e32 v202, v154, v114
	v_fmac_f32_e32 v203, v155, v115
	global_store_dwordx4 v236, v[188:191], s[32:33] offset:0 nt
	global_store_dwordx4 v236, v[192:195], s[32:33] offset:1024 nt
	global_store_dwordx4 v236, v[196:199], s[32:33] offset:2048 nt
	global_store_dwordx4 v236, v[200:203], s[32:33] offset:3072 nt
	s_cmp_lt_u32 s6, s7
	s_cbranch_scc0 .Lrp21_done
	s_sub_u32 s9, s6, 0x2000
	s_ashr_i32 s9, s9, 10
	s_add_i32 s9, s9, 1
	s_max_i32 s9, s9, 0
	s_cmp_eq_u32 s9, s8
	s_cbranch_scc1 .Lrp21_same1
	s_mov_b32 s8, s9
	s_add_i32 s9, s8, 3
	s_mul_i32 s9, s9, 0x6000
	s_add_u32 s36, s22, s9
	s_addc_u32 s37, s23, 0
	s_add_u32 s38, s36, 0x5000
	s_addc_u32 s39, s37, 0
	global_load_dwordx4 v[32:35], v236, s[38:39] offset:0
	global_load_dwordx4 v[36:39], v236, s[38:39] offset:1024
	global_load_dwordx4 v[40:43], v236, s[38:39] offset:2048
	global_load_dwordx4 v[44:47], v236, s[38:39] offset:3072
	global_load_dwordx4 v[48:51], v236, s[10:11] offset:0
	global_load_dwordx4 v[52:55], v236, s[10:11] offset:1024
	global_load_dwordx4 v[56:59], v236, s[10:11] offset:2048
	global_load_dwordx4 v[64:67], v236, s[10:11] offset:3072
	s_waitcnt vmcnt(0)
	v_mul_f32_e32 v140, v32, v48
	v_mul_f32_e32 v141, v33, v49
	v_mul_f32_e32 v142, v34, v50
	v_mul_f32_e32 v143, v35, v51
	v_mul_f32_e32 v144, v36, v52
	v_mul_f32_e32 v145, v37, v53
	v_mul_f32_e32 v146, v38, v54
	v_mul_f32_e32 v147, v39, v55
	v_mul_f32_e32 v148, v40, v56
	v_mul_f32_e32 v149, v41, v57
	v_mul_f32_e32 v150, v42, v58
	v_mul_f32_e32 v151, v43, v59
	v_mul_f32_e32 v152, v44, v64
	v_mul_f32_e32 v153, v45, v65
	v_mul_f32_e32 v154, v46, v66
	v_mul_f32_e32 v155, v47, v67

.Lrp21_go1:
	v_lshlrev_b32_e32 v100, 16, v228
	v_and_b32_e32 v101, 0xffff0000, v228
	v_lshlrev_b32_e32 v102, 16, v229
	v_and_b32_e32 v103, 0xffff0000, v229
	v_lshlrev_b32_e32 v104, 16, v230
	v_and_b32_e32 v105, 0xffff0000, v230
	v_lshlrev_b32_e32 v106, 16, v231
	v_and_b32_e32 v107, 0xffff0000, v231
	v_lshlrev_b32_e32 v108, 16, v232
	v_and_b32_e32 v109, 0xffff0000, v232
	v_lshlrev_b32_e32 v110, 16, v233
	v_and_b32_e32 v111, 0xffff0000, v233
	v_lshlrev_b32_e32 v112, 16, v234
	v_and_b32_e32 v113, 0xffff0000, v234
	v_lshlrev_b32_e32 v114, 16, v235
	v_and_b32_e32 v115, 0xffff0000, v235
	v_mul_f32_e32 v132, v100, v100
	v_mul_f32_e32 v133, v101, v101
	v_fmac_f32_e32 v132, v102, v102
	v_fmac_f32_e32 v133, v103, v103
	v_fmac_f32_e32 v132, v104, v104
	v_fmac_f32_e32 v133, v105, v105
	v_fmac_f32_e32 v132, v106, v106
	v_fmac_f32_e32 v133, v107, v107
	v_fmac_f32_e32 v132, v108, v108
	v_fmac_f32_e32 v133, v109, v109
	v_fmac_f32_e32 v132, v110, v110
	v_fmac_f32_e32 v133, v111, v111
	v_fmac_f32_e32 v132, v112, v112
	v_fmac_f32_e32 v133, v113, v113
	v_fmac_f32_e32 v132, v114, v114
	v_fmac_f32_e32 v133, v115, v115
	v_add_f32_e32 v132, v132, v133
	s_nop 1
	v_add_f32_dpp v132, v132, v132 quad_perm:[1,0,3,2] row_mask:0xf bank_mask:0xf bound_ctrl:1
	s_nop 1
	v_add_f32_dpp v132, v132, v132 quad_perm:[2,3,0,1] row_mask:0xf bank_mask:0xf bound_ctrl:1
	s_nop 1
	v_add_f32_dpp v132, v132, v132 row_ror:4 row_mask:0xf bank_mask:0xf bound_ctrl:1
	s_nop 1
	v_add_f32_dpp v132, v132, v132 row_ror:8 row_mask:0xf bank_mask:0xf bound_ctrl:1
	s_nop 1
	v_readlane_b32 s9, v132, 0
	v_readlane_b32 s38, v132, 16
	v_readlane_b32 s39, v132, 32
	v_readlane_b32 s40, v132, 48
	s_nop 2
	v_mov_b32_e32 v132, s9
	v_add_f32_e32 v132, s38, v132
	v_mov_b32_e32 v135, s39
	v_add_f32_e32 v135, s40, v135
	v_add_f32_e32 v132, v132, v135
	v_fmamk_f32 v132, v132, 0x3a800000, v238
	v_rsq_f32_e32 v132, v132
	s_nop 0
	v_mul_f32_e32 v100, v100, v132
	v_mul_f32_e32 v101, v101, v132
	v_mul_f32_e32 v102, v102, v132
	v_mul_f32_e32 v103, v103, v132
	v_mul_f32_e32 v104, v104, v132
	v_mul_f32_e32 v105, v105, v132
	v_mul_f32_e32 v106, v106, v132
	v_mul_f32_e32 v107, v107, v132
	v_mul_f32_e32 v108, v108, v132
	v_mul_f32_e32 v109, v109, v132
	v_mul_f32_e32 v110, v110, v132
	v_mul_f32_e32 v111, v111, v132
	v_mul_f32_e32 v112, v112, v132
	v_mul_f32_e32 v113, v113, v132
	v_mul_f32_e32 v114, v114, v132
	v_mul_f32_e32 v115, v115, v132
	v_fmac_f32_e32 v212, v140, v100
	v_fmac_f32_e32 v213, v141, v101
	v_fmac_f32_e32 v214, v142, v102
	v_fmac_f32_e32 v215, v143, v103
	v_fmac_f32_e32 v216, v144, v104
	v_fmac_f32_e32 v217, v145, v105
	v_fmac_f32_e32 v218, v146, v106
	v_fmac_f32_e32 v219, v147, v107
	v_fmac_f32_e32 v220, v148, v108
	v_fmac_f32_e32 v221, v149, v109
	v_fmac_f32_e32 v222, v150, v110
	v_fmac_f32_e32 v223, v151, v111
	v_fmac_f32_e32 v224, v152, v112
	v_fmac_f32_e32 v225, v153, v113
	v_fmac_f32_e32 v226, v154, v114
	v_fmac_f32_e32 v227, v155, v115
	global_store_dwordx4 v236, v[212:215], s[32:33] offset:0 nt
	global_store_dwordx4 v236, v[216:219], s[32:33] offset:1024 nt
	global_store_dwordx4 v236, v[220:223], s[32:33] offset:2048 nt
	global_store_dwordx4 v236, v[224:227], s[32:33] offset:3072 nt
	s_cmp_lt_u32 s6, s7
	s_cbranch_scc1 .Lrp21_loop
